# v29 + nt policy on EpiScale output stores (PROJ q|g and QKV)
# baseline (speedup 1.0000x reference)
; #define PG8_LAS __attribute__((address_space(3)))
; __device__ __forceinline__ unsigned cvt_pk_bf16(float lo, float hi) { unsigned r; asm volatile("v_cvt_pk_bf16_f32 %0, %1, %2" : "=v"(r) : "v"(lo), "v"(hi)); return r; }
;     __device__ __forceinline__ void operator()(const f32x4 (&acc)[2][2][4][2], const Unit& u, int wr, int wc, int fr, int fq, PG8_LAS unsigned char* lds, int wid, int lane) const {
;     ...
;         const float cs = (mode == 2 && colt < 2048) ? 0.125f : 1.0f;
;         asm volatile("s_waitcnt lgkmcnt(0)" ::: "memory"); __builtin_amdgcn_s_barrier(); asm volatile("" ::: "memory");
;         bf16_t* obase = O + (size_t)(u.pm * BM + wr * 64 + (lane >> 2)) * ldc + colt + wc * 32 + 8 * (lane & 3);
; #pragma unroll
;         for (int ai = 0; ai < 2; ++ai)
; #pragma unroll
;             for (int m = 0; m < 4; ++m) { const float rs = tbl[ai * HALF + wr * 64 + m * 16 + fr];
; #pragma unroll
;                 for (int bj = 0; bj < 2; ++bj) { const f32x4 v0 = (acc[ai][bj][m][0] * rs + bv[bj][0]) * cs, v1 = (acc[ai][bj][m][1] * rs + bv[bj][1]) * cs;
;                     u32x4 w; w.x = cvt_pk_bf16(v0[0], v0[1]); w.y = cvt_pk_bf16(v0[2], v0[3]); w.z = cvt_pk_bf16(v1[0], v1[1]); w.w = cvt_pk_bf16(v1[2], v1[3]);
;                     *(PG8_LAS u32x4*)(st + fr * 80 + fq * 16) = w;
;                     const u32x4 x = *(const PG8_LAS u32x4*)(st + (lane >> 2) * 80 + (lane & 3) * 16);
;                     *(u32x4*)(obase + (size_t)(ai * HALF + m * 16) * ldc + bj * HALF) = x; } }
.LBB0_514:
	s_cmp_lt_i32 s79, 8
	v_readlane_b32 s42, v252, 38
	v_lshl_add_u32 v163, s37, 8, v168
	s_cselect_b64 s[4:5], -1, 0
	v_readlane_b32 s43, v252, 39
	v_ashrrev_i32_e32 v173, 31, v163
	s_and_b64 vcc, s[42:43], s[4:5]
	s_waitcnt lgkmcnt(0)
	s_barrier
	v_mul_lo_u32 v173, s26, v173
	v_mul_lo_u32 v176, s27, v163
	v_mad_u64_u32 v[174:175], s[4:5], s26, v163, 0
	v_add3_u32 v175, v175, v173, v176
	ds_read_b32 v176, v169
	v_mov_b32_e32 v162, 0x3e000000
	v_cndmask_b32_e32 v162, 1.0, v162, vcc
	v_readlane_b32 s4, v252, 45
	v_readlane_b32 s5, v252, 46
	s_waitcnt vmcnt(0) lgkmcnt(0)
	v_pk_fma_f32 v[128:129], v[128:129], v[176:177], v[136:137] op_sel_hi:[1,0,1]
	v_pk_fma_f32 v[130:131], v[130:131], v[176:177], v[138:139] op_sel_hi:[1,0,1]
	v_pk_fma_f32 v[132:133], v[132:133], v[176:177], v[144:145] op_sel_hi:[1,0,1]
	v_pk_fma_f32 v[134:135], v[134:135], v[176:177], v[146:147] op_sel_hi:[1,0,1]
	v_pk_mul_f32 v[178:179], v[162:163], v[130:131] op_sel_hi:[0,1]
	v_pk_mul_f32 v[130:131], v[162:163], v[128:129] op_sel_hi:[0,1]
	v_pk_mul_f32 v[134:135], v[162:163], v[134:135] op_sel_hi:[0,1]
	v_pk_mul_f32 v[132:133], v[162:163], v[132:133] op_sel_hi:[0,1]
	v_cvt_pk_bf16_f32 v128, v132, v133
	v_cvt_pk_bf16_f32 v129, v134, v135
	v_cvt_pk_bf16_f32 v130, v130, v131
	v_cvt_pk_bf16_f32 v131, v178, v179
	ds_write_b128 v171, v[128:131]
	ds_read_b128 v[128:131], v172
	v_lshl_add_u64 v[174:175], v[174:175], 1, s[4:5]
	s_ashr_i32 s1, s0, 31
	v_lshl_add_u64 v[174:175], s[0:1], 1, v[174:175]
	v_lshl_add_u64 v[174:175], v[174:175], 0, s[20:21]
	v_lshl_add_u64 v[174:175], v[174:175], 0, v[0:1]
	v_pk_fma_f32 v[120:121], v[120:121], v[176:177], v[140:141] op_sel_hi:[1,0,1]
	v_pk_fma_f32 v[122:123], v[122:123], v[176:177], v[142:143] op_sel_hi:[1,0,1]
	s_waitcnt lgkmcnt(0)
	global_store_dwordx4 v[174:175], v[128:131], off nt
	v_pk_fma_f32 v[124:125], v[124:125], v[176:177], v[148:149] op_sel_hi:[1,0,1]
	v_pk_fma_f32 v[126:127], v[126:127], v[176:177], v[150:151] op_sel_hi:[1,0,1]
	v_pk_mul_f32 v[128:129], v[162:163], v[122:123] op_sel_hi:[0,1]
	v_pk_mul_f32 v[122:123], v[162:163], v[120:121] op_sel_hi:[0,1]
	v_pk_mul_f32 v[126:127], v[162:163], v[126:127] op_sel_hi:[0,1]
	v_pk_mul_f32 v[124:125], v[162:163], v[124:125] op_sel_hi:[0,1]
	v_cvt_pk_bf16_f32 v120, v124, v125
	v_cvt_pk_bf16_f32 v121, v126, v127
	v_cvt_pk_bf16_f32 v122, v122, v123
	v_cvt_pk_bf16_f32 v123, v128, v129
	ds_write_b128 v171, v[120:123]
	ds_read_b128 v[120:123], v172
	s_mov_b64 s[0:1], -1
	s_and_b64 vcc, exec, s[2:3]
	s_waitcnt lgkmcnt(0)
	global_store_dwordx4 v[174:175], v[120:123], off offset:256 nt
	ds_read_b32 v120, v169 offset:64
	s_waitcnt lgkmcnt(0)
	v_pk_fma_f32 v[112:113], v[112:113], v[120:121], v[136:137] op_sel_hi:[1,0,1]
	v_pk_fma_f32 v[114:115], v[114:115], v[120:121], v[138:139] op_sel_hi:[1,0,1]
	v_pk_fma_f32 v[116:117], v[116:117], v[120:121], v[144:145] op_sel_hi:[1,0,1]
	v_pk_fma_f32 v[118:119], v[118:119], v[120:121], v[146:147] op_sel_hi:[1,0,1]
	v_pk_mul_f32 v[122:123], v[162:163], v[114:115] op_sel_hi:[0,1]
	v_pk_mul_f32 v[114:115], v[162:163], v[112:113] op_sel_hi:[0,1]
	v_pk_mul_f32 v[118:119], v[162:163], v[118:119] op_sel_hi:[0,1]
	v_pk_mul_f32 v[116:117], v[162:163], v[116:117] op_sel_hi:[0,1]
	v_cvt_pk_bf16_f32 v112, v116, v117
	v_cvt_pk_bf16_f32 v113, v118, v119
	v_cvt_pk_bf16_f32 v114, v114, v115
	v_cvt_pk_bf16_f32 v115, v122, v123
	ds_write_b128 v171, v[112:115]
	ds_read_b128 v[112:115], v172
	v_lshl_add_u64 v[116:117], v[174:175], 0, s[54:55]
	v_pk_fma_f32 v[104:105], v[104:105], v[120:121], v[140:141] op_sel_hi:[1,0,1]
	v_pk_fma_f32 v[106:107], v[106:107], v[120:121], v[142:143] op_sel_hi:[1,0,1]
	v_pk_fma_f32 v[108:109], v[108:109], v[120:121], v[148:149] op_sel_hi:[1,0,1]
	s_waitcnt lgkmcnt(0)
	global_store_dwordx4 v[116:117], v[112:115], off nt
	v_pk_fma_f32 v[110:111], v[110:111], v[120:121], v[150:151] op_sel_hi:[1,0,1]
	v_pk_mul_f32 v[108:109], v[162:163], v[108:109] op_sel_hi:[0,1]
	v_pk_mul_f32 v[112:113], v[162:163], v[106:107] op_sel_hi:[0,1]
	v_pk_mul_f32 v[106:107], v[162:163], v[104:105] op_sel_hi:[0,1]
	v_pk_mul_f32 v[110:111], v[162:163], v[110:111] op_sel_hi:[0,1]
	v_cvt_pk_bf16_f32 v104, v108, v109
	v_cvt_pk_bf16_f32 v105, v110, v111
	v_cvt_pk_bf16_f32 v106, v106, v107
	v_cvt_pk_bf16_f32 v107, v112, v113
	ds_write_b128 v171, v[104:107]
	ds_read_b128 v[104:107], v172
	s_waitcnt lgkmcnt(0)
	global_store_dwordx4 v[116:117], v[104:107], off offset:256 nt
	ds_read_b32 v104, v169 offset:128
	s_waitcnt lgkmcnt(0)
	v_pk_fma_f32 v[96:97], v[96:97], v[104:105], v[136:137] op_sel_hi:[1,0,1]
	v_pk_fma_f32 v[98:99], v[98:99], v[104:105], v[138:139] op_sel_hi:[1,0,1]
	v_pk_fma_f32 v[100:101], v[100:101], v[104:105], v[144:145] op_sel_hi:[1,0,1]
	v_pk_fma_f32 v[102:103], v[102:103], v[104:105], v[146:147] op_sel_hi:[1,0,1]
	v_pk_mul_f32 v[106:107], v[162:163], v[98:99] op_sel_hi:[0,1]
	v_pk_mul_f32 v[98:99], v[162:163], v[96:97] op_sel_hi:[0,1]
	v_pk_mul_f32 v[102:103], v[162:163], v[102:103] op_sel_hi:[0,1]
	v_pk_mul_f32 v[100:101], v[162:163], v[100:101] op_sel_hi:[0,1]
	v_cvt_pk_bf16_f32 v96, v100, v101
	v_cvt_pk_bf16_f32 v97, v102, v103
	v_cvt_pk_bf16_f32 v98, v98, v99
	v_cvt_pk_bf16_f32 v99, v106, v107
	ds_write_b128 v171, v[96:99]
	ds_read_b128 v[96:99], v172
	v_lshl_add_u64 v[100:101], v[116:117], 0, s[54:55]
	v_pk_fma_f32 v[88:89], v[88:89], v[104:105], v[140:141] op_sel_hi:[1,0,1]
	v_pk_fma_f32 v[90:91], v[90:91], v[104:105], v[142:143] op_sel_hi:[1,0,1]
	v_pk_fma_f32 v[92:93], v[92:93], v[104:105], v[148:149] op_sel_hi:[1,0,1]
	s_waitcnt lgkmcnt(0)
; #define PG8_LAS __attribute__((address_space(3)))
; __device__ __forceinline__ unsigned cvt_pk_bf16(float lo, float hi) { unsigned r; asm volatile("v_cvt_pk_bf16_f32 %0, %1, %2" : "=v"(r) : "v"(lo), "v"(hi)); return r; }
;     __device__ __forceinline__ void operator()(const f32x4 (&acc)[2][2][4][2], const Unit& u, int wr, int wc, int fr, int fq, PG8_LAS unsigned char* lds, int wid, int lane) const {
;     ...
;         const float cs = (mode == 2 && colt < 2048) ? 0.125f : 1.0f;
;         asm volatile("s_waitcnt lgkmcnt(0)" ::: "memory"); __builtin_amdgcn_s_barrier(); asm volatile("" ::: "memory");
;         bf16_t* obase = O + (size_t)(u.pm * BM + wr * 64 + (lane >> 2)) * ldc + colt + wc * 32 + 8 * (lane & 3);
; #pragma unroll
;         for (int ai = 0; ai < 2; ++ai)
; #pragma unroll
;             for (int m = 0; m < 4; ++m) { const float rs = tbl[ai * HALF + wr * 64 + m * 16 + fr];
; #pragma unroll
;                 for (int bj = 0; bj < 2; ++bj) { const f32x4 v0 = (acc[ai][bj][m][0] * rs + bv[bj][0]) * cs, v1 = (acc[ai][bj][m][1] * rs + bv[bj][1]) * cs;
;                     u32x4 w; w.x = cvt_pk_bf16(v0[0], v0[1]); w.y = cvt_pk_bf16(v0[2], v0[3]); w.z = cvt_pk_bf16(v1[0], v1[1]); w.w = cvt_pk_bf16(v1[2], v1[3]);
;                     *(PG8_LAS u32x4*)(st + fr * 80 + fq * 16) = w;
;                     const u32x4 x = *(const PG8_LAS u32x4*)(st + (lane >> 2) * 80 + (lane & 3) * 16);
;                     *(u32x4*)(obase + (size_t)(ai * HALF + m * 16) * ldc + bj * HALF) = x; } }
	global_store_dwordx4 v[100:101], v[96:99], off nt
	v_pk_fma_f32 v[94:95], v[94:95], v[104:105], v[150:151] op_sel_hi:[1,0,1]
	v_pk_mul_f32 v[92:93], v[162:163], v[92:93] op_sel_hi:[0,1]
	v_pk_mul_f32 v[96:97], v[162:163], v[90:91] op_sel_hi:[0,1]
	v_pk_mul_f32 v[90:91], v[162:163], v[88:89] op_sel_hi:[0,1]
	v_pk_mul_f32 v[94:95], v[162:163], v[94:95] op_sel_hi:[0,1]
	v_cvt_pk_bf16_f32 v88, v92, v93
	v_cvt_pk_bf16_f32 v89, v94, v95
	v_cvt_pk_bf16_f32 v90, v90, v91
	v_cvt_pk_bf16_f32 v91, v96, v97
	ds_write_b128 v171, v[88:91]
	ds_read_b128 v[88:91], v172
	s_waitcnt lgkmcnt(0)
	global_store_dwordx4 v[100:101], v[88:91], off offset:256 nt
	ds_read_b32 v88, v169 offset:192
	s_waitcnt lgkmcnt(0)
	v_pk_fma_f32 v[80:81], v[80:81], v[88:89], v[136:137] op_sel_hi:[1,0,1]
	v_pk_fma_f32 v[82:83], v[82:83], v[88:89], v[138:139] op_sel_hi:[1,0,1]
	v_pk_fma_f32 v[84:85], v[84:85], v[88:89], v[144:145] op_sel_hi:[1,0,1]
	v_pk_fma_f32 v[86:87], v[86:87], v[88:89], v[146:147] op_sel_hi:[1,0,1]
	v_pk_mul_f32 v[90:91], v[162:163], v[82:83] op_sel_hi:[0,1]
	v_pk_mul_f32 v[82:83], v[162:163], v[80:81] op_sel_hi:[0,1]
	v_pk_mul_f32 v[86:87], v[162:163], v[86:87] op_sel_hi:[0,1]
	v_pk_mul_f32 v[84:85], v[162:163], v[84:85] op_sel_hi:[0,1]
	v_cvt_pk_bf16_f32 v80, v84, v85
	v_cvt_pk_bf16_f32 v81, v86, v87
	v_cvt_pk_bf16_f32 v82, v82, v83
	v_cvt_pk_bf16_f32 v83, v90, v91
	ds_write_b128 v171, v[80:83]
	ds_read_b128 v[80:83], v172
	v_lshl_add_u64 v[84:85], v[100:101], 0, s[54:55]
	v_pk_fma_f32 v[72:73], v[72:73], v[88:89], v[140:141] op_sel_hi:[1,0,1]
	v_pk_fma_f32 v[74:75], v[74:75], v[88:89], v[142:143] op_sel_hi:[1,0,1]
	v_pk_fma_f32 v[76:77], v[76:77], v[88:89], v[148:149] op_sel_hi:[1,0,1]
	s_waitcnt lgkmcnt(0)
	global_store_dwordx4 v[84:85], v[80:83], off nt
	v_pk_fma_f32 v[78:79], v[78:79], v[88:89], v[150:151] op_sel_hi:[1,0,1]
	v_pk_mul_f32 v[76:77], v[162:163], v[76:77] op_sel_hi:[0,1]
	v_pk_mul_f32 v[80:81], v[162:163], v[74:75] op_sel_hi:[0,1]
	v_pk_mul_f32 v[74:75], v[162:163], v[72:73] op_sel_hi:[0,1]
	v_pk_mul_f32 v[78:79], v[162:163], v[78:79] op_sel_hi:[0,1]
	v_cvt_pk_bf16_f32 v72, v76, v77
	v_cvt_pk_bf16_f32 v73, v78, v79
	v_cvt_pk_bf16_f32 v74, v74, v75
	v_cvt_pk_bf16_f32 v75, v80, v81
	ds_write_b128 v171, v[72:75]
	ds_read_b128 v[72:75], v172
	s_waitcnt lgkmcnt(0)
	global_store_dwordx4 v[84:85], v[72:75], off offset:256 nt
	ds_read_b32 v72, v169 offset:512
	s_waitcnt lgkmcnt(0)
	v_pk_fma_f32 v[64:65], v[64:65], v[72:73], v[136:137] op_sel_hi:[1,0,1]
	v_pk_fma_f32 v[66:67], v[66:67], v[72:73], v[138:139] op_sel_hi:[1,0,1]
	v_pk_fma_f32 v[68:69], v[68:69], v[72:73], v[144:145] op_sel_hi:[1,0,1]
	v_pk_fma_f32 v[70:71], v[70:71], v[72:73], v[146:147] op_sel_hi:[1,0,1]
	v_pk_mul_f32 v[74:75], v[162:163], v[66:67] op_sel_hi:[0,1]
	v_pk_mul_f32 v[66:67], v[162:163], v[64:65] op_sel_hi:[0,1]
	v_pk_mul_f32 v[70:71], v[162:163], v[70:71] op_sel_hi:[0,1]
	v_pk_mul_f32 v[68:69], v[162:163], v[68:69] op_sel_hi:[0,1]
	v_cvt_pk_bf16_f32 v64, v68, v69
	v_cvt_pk_bf16_f32 v65, v70, v71
	v_cvt_pk_bf16_f32 v66, v66, v67
	v_cvt_pk_bf16_f32 v67, v74, v75
	ds_write_b128 v171, v[64:67]
	ds_read_b128 v[64:67], v172
	v_lshl_add_u64 v[68:69], v[84:85], 0, s[16:17]
	v_pk_fma_f32 v[56:57], v[56:57], v[72:73], v[140:141] op_sel_hi:[1,0,1]
	v_pk_fma_f32 v[58:59], v[58:59], v[72:73], v[142:143] op_sel_hi:[1,0,1]
	v_pk_fma_f32 v[60:61], v[60:61], v[72:73], v[148:149] op_sel_hi:[1,0,1]
	s_waitcnt lgkmcnt(0)
	global_store_dwordx4 v[68:69], v[64:67], off nt
	v_pk_fma_f32 v[62:63], v[62:63], v[72:73], v[150:151] op_sel_hi:[1,0,1]
	v_pk_mul_f32 v[60:61], v[162:163], v[60:61] op_sel_hi:[0,1]
	v_pk_mul_f32 v[64:65], v[162:163], v[58:59] op_sel_hi:[0,1]
	v_pk_mul_f32 v[58:59], v[162:163], v[56:57] op_sel_hi:[0,1]
	v_pk_mul_f32 v[62:63], v[162:163], v[62:63] op_sel_hi:[0,1]
	v_cvt_pk_bf16_f32 v56, v60, v61
	v_cvt_pk_bf16_f32 v57, v62, v63
	v_cvt_pk_bf16_f32 v58, v58, v59
	v_cvt_pk_bf16_f32 v59, v64, v65
	ds_write_b128 v171, v[56:59]
	ds_read_b128 v[56:59], v172
	s_waitcnt lgkmcnt(0)
	global_store_dwordx4 v[68:69], v[56:59], off offset:256 nt
	ds_read_b32 v56, v169 offset:576
	s_waitcnt lgkmcnt(0)
	v_pk_fma_f32 v[48:49], v[48:49], v[56:57], v[136:137] op_sel_hi:[1,0,1]
	v_pk_fma_f32 v[50:51], v[50:51], v[56:57], v[138:139] op_sel_hi:[1,0,1]
	v_pk_fma_f32 v[52:53], v[52:53], v[56:57], v[144:145] op_sel_hi:[1,0,1]
	v_pk_fma_f32 v[54:55], v[54:55], v[56:57], v[146:147] op_sel_hi:[1,0,1]
	v_pk_mul_f32 v[58:59], v[162:163], v[50:51] op_sel_hi:[0,1]
	v_pk_mul_f32 v[50:51], v[162:163], v[48:49] op_sel_hi:[0,1]
	v_pk_mul_f32 v[54:55], v[162:163], v[54:55] op_sel_hi:[0,1]
	v_pk_mul_f32 v[52:53], v[162:163], v[52:53] op_sel_hi:[0,1]
	v_cvt_pk_bf16_f32 v48, v52, v53
	v_cvt_pk_bf16_f32 v49, v54, v55
	v_cvt_pk_bf16_f32 v50, v50, v51
	v_cvt_pk_bf16_f32 v51, v58, v59
	ds_write_b128 v171, v[48:51]
	ds_read_b128 v[48:51], v172
	v_lshl_add_u64 v[52:53], v[68:69], 0, s[54:55]
	v_pk_fma_f32 v[40:41], v[40:41], v[56:57], v[140:141] op_sel_hi:[1,0,1]
	v_pk_fma_f32 v[42:43], v[42:43], v[56:57], v[142:143] op_sel_hi:[1,0,1]
	v_pk_fma_f32 v[44:45], v[44:45], v[56:57], v[148:149] op_sel_hi:[1,0,1]
	s_waitcnt lgkmcnt(0)
; #define PG8_LAS __attribute__((address_space(3)))
; __device__ __forceinline__ unsigned cvt_pk_bf16(float lo, float hi) { unsigned r; asm volatile("v_cvt_pk_bf16_f32 %0, %1, %2" : "=v"(r) : "v"(lo), "v"(hi)); return r; }
; #define PG8_BAR __builtin_amdgcn_s_barrier()
;     __device__ __forceinline__ void operator()(const f32x4 (&acc)[2][2][4][2], const Unit& u, int wr, int wc, int fr, int fq, PG8_LAS unsigned char* lds, int wid, int lane) const {
;     ...
;         const float cs = (mode == 2 && colt < 2048) ? 0.125f : 1.0f;
;         asm volatile("s_waitcnt lgkmcnt(0)" ::: "memory"); __builtin_amdgcn_s_barrier(); asm volatile("" ::: "memory");
;         bf16_t* obase = O + (size_t)(u.pm * BM + wr * 64 + (lane >> 2)) * ldc + colt + wc * 32 + 8 * (lane & 3);
; #pragma unroll
;         for (int ai = 0; ai < 2; ++ai)
; #pragma unroll
;             for (int m = 0; m < 4; ++m) { const float rs = tbl[ai * HALF + wr * 64 + m * 16 + fr];
; #pragma unroll
;                 for (int bj = 0; bj < 2; ++bj) { const f32x4 v0 = (acc[ai][bj][m][0] * rs + bv[bj][0]) * cs, v1 = (acc[ai][bj][m][1] * rs + bv[bj][1]) * cs;
;                     u32x4 w; w.x = cvt_pk_bf16(v0[0], v0[1]); w.y = cvt_pk_bf16(v0[2], v0[3]); w.z = cvt_pk_bf16(v1[0], v1[1]); w.w = cvt_pk_bf16(v1[2], v1[3]);
;                     *(PG8_LAS u32x4*)(st + fr * 80 + fq * 16) = w;
;                     const u32x4 x = *(const PG8_LAS u32x4*)(st + (lane >> 2) * 80 + (lane & 3) * 16);
;                     *(u32x4*)(obase + (size_t)(ai * HALF + m * 16) * ldc + bj * HALF) = x; } }
; template <class Epi, class Sched, bool ALIGN_EPI = false, bool SP2 = false>
; __device__ __forceinline__ void gemm_phase(PG8_LAS unsigned char* lds, const Gemm g, const Sched& S, const Epi& E) {
;     ...
;         if constexpr (ALIGN_EPI) { if (wr == 0) PG8_BAR; }
;         if constexpr (!Epi::AFTER_DRAIN) { E(acc, cur, wr, wc, fr, fq, lds, wid, lane); S.done(cur); }
;         if (!has_next) break;
; #pragma unroll
;         for (int a = 0; a < 2; ++a)
; #pragma unroll
;             for (int b = 0; b < 2; ++b)
; #pragma unroll
;                 for (int m = 0; m < 4; ++m)
; #pragma unroll
;                     for (int n = 0; n < 2; ++n) acc[a][b][m][n] = (f32x4){0.f, 0.f, 0.f, 0.f};
;         cur = nxt; cA = nA; cB = nB; ++ui;
;         if constexpr (ALIGN_EPI) { if (wr == 1) PG8_BAR; }
;     }
	global_store_dwordx4 v[52:53], v[48:51], off nt
	v_pk_fma_f32 v[46:47], v[46:47], v[56:57], v[150:151] op_sel_hi:[1,0,1]
	v_pk_mul_f32 v[44:45], v[162:163], v[44:45] op_sel_hi:[0,1]
	v_pk_mul_f32 v[48:49], v[162:163], v[42:43] op_sel_hi:[0,1]
	v_pk_mul_f32 v[42:43], v[162:163], v[40:41] op_sel_hi:[0,1]
	v_pk_mul_f32 v[46:47], v[162:163], v[46:47] op_sel_hi:[0,1]
	v_cvt_pk_bf16_f32 v40, v44, v45
	v_cvt_pk_bf16_f32 v41, v46, v47
	v_cvt_pk_bf16_f32 v42, v42, v43
	v_cvt_pk_bf16_f32 v43, v48, v49
	ds_write_b128 v171, v[40:43]
	ds_read_b128 v[40:43], v172
	s_waitcnt lgkmcnt(0)
	global_store_dwordx4 v[52:53], v[40:43], off offset:256 nt
	ds_read_b32 v40, v169 offset:640
	s_waitcnt lgkmcnt(0)
	v_pk_fma_f32 v[32:33], v[32:33], v[40:41], v[136:137] op_sel_hi:[1,0,1]
	v_pk_fma_f32 v[34:35], v[34:35], v[40:41], v[138:139] op_sel_hi:[1,0,1]
	v_pk_fma_f32 v[36:37], v[36:37], v[40:41], v[144:145] op_sel_hi:[1,0,1]
	v_pk_fma_f32 v[38:39], v[38:39], v[40:41], v[146:147] op_sel_hi:[1,0,1]
	v_pk_mul_f32 v[42:43], v[162:163], v[34:35] op_sel_hi:[0,1]
	v_pk_mul_f32 v[34:35], v[162:163], v[32:33] op_sel_hi:[0,1]
	v_pk_mul_f32 v[38:39], v[162:163], v[38:39] op_sel_hi:[0,1]
	v_pk_mul_f32 v[36:37], v[162:163], v[36:37] op_sel_hi:[0,1]
	v_cvt_pk_bf16_f32 v32, v36, v37
	v_cvt_pk_bf16_f32 v33, v38, v39
	v_cvt_pk_bf16_f32 v34, v34, v35
	v_cvt_pk_bf16_f32 v35, v42, v43
	ds_write_b128 v171, v[32:35]
	ds_read_b128 v[32:35], v172
	v_lshl_add_u64 v[36:37], v[52:53], 0, s[54:55]
	v_pk_fma_f32 v[24:25], v[24:25], v[40:41], v[140:141] op_sel_hi:[1,0,1]
	v_pk_fma_f32 v[26:27], v[26:27], v[40:41], v[142:143] op_sel_hi:[1,0,1]
	v_pk_fma_f32 v[28:29], v[28:29], v[40:41], v[148:149] op_sel_hi:[1,0,1]
	s_waitcnt lgkmcnt(0)
	global_store_dwordx4 v[36:37], v[32:35], off nt
	v_pk_fma_f32 v[30:31], v[30:31], v[40:41], v[150:151] op_sel_hi:[1,0,1]
	v_pk_mul_f32 v[28:29], v[162:163], v[28:29] op_sel_hi:[0,1]
	v_pk_mul_f32 v[32:33], v[162:163], v[26:27] op_sel_hi:[0,1]
	v_pk_mul_f32 v[26:27], v[162:163], v[24:25] op_sel_hi:[0,1]
	v_pk_mul_f32 v[30:31], v[162:163], v[30:31] op_sel_hi:[0,1]
	v_cvt_pk_bf16_f32 v24, v28, v29
	v_cvt_pk_bf16_f32 v25, v30, v31
	v_cvt_pk_bf16_f32 v26, v26, v27
	v_cvt_pk_bf16_f32 v27, v32, v33
	ds_write_b128 v171, v[24:27]
	ds_read_b128 v[24:27], v172
	s_waitcnt lgkmcnt(0)
	global_store_dwordx4 v[36:37], v[24:27], off offset:256 nt
	ds_read_b32 v24, v169 offset:704
	s_waitcnt lgkmcnt(0)
	v_pk_fma_f32 v[16:17], v[16:17], v[24:25], v[136:137] op_sel_hi:[1,0,1]
	v_pk_fma_f32 v[18:19], v[18:19], v[24:25], v[138:139] op_sel_hi:[1,0,1]
	v_pk_fma_f32 v[20:21], v[20:21], v[24:25], v[144:145] op_sel_hi:[1,0,1]
	v_pk_fma_f32 v[22:23], v[22:23], v[24:25], v[146:147] op_sel_hi:[1,0,1]
	v_pk_mul_f32 v[26:27], v[162:163], v[18:19] op_sel_hi:[0,1]
	v_pk_mul_f32 v[18:19], v[162:163], v[16:17] op_sel_hi:[0,1]
	v_pk_mul_f32 v[22:23], v[162:163], v[22:23] op_sel_hi:[0,1]
	v_pk_mul_f32 v[20:21], v[162:163], v[20:21] op_sel_hi:[0,1]
	v_cvt_pk_bf16_f32 v16, v20, v21
	v_cvt_pk_bf16_f32 v17, v22, v23
	v_cvt_pk_bf16_f32 v18, v18, v19
	v_cvt_pk_bf16_f32 v19, v26, v27
	ds_write_b128 v171, v[16:19]
	ds_read_b128 v[16:19], v172
	v_lshl_add_u64 v[20:21], v[36:37], 0, s[54:55]
	v_pk_fma_f32 v[8:9], v[8:9], v[24:25], v[140:141] op_sel_hi:[1,0,1]
	v_pk_fma_f32 v[10:11], v[10:11], v[24:25], v[142:143] op_sel_hi:[1,0,1]
	v_pk_fma_f32 v[12:13], v[12:13], v[24:25], v[148:149] op_sel_hi:[1,0,1]
	s_waitcnt lgkmcnt(0)
	global_store_dwordx4 v[20:21], v[16:19], off nt
	v_pk_fma_f32 v[14:15], v[14:15], v[24:25], v[150:151] op_sel_hi:[1,0,1]
	v_pk_mul_f32 v[12:13], v[162:163], v[12:13] op_sel_hi:[0,1]
	v_pk_mul_f32 v[16:17], v[162:163], v[10:11] op_sel_hi:[0,1]
	v_pk_mul_f32 v[10:11], v[162:163], v[8:9] op_sel_hi:[0,1]
	v_pk_mul_f32 v[14:15], v[162:163], v[14:15] op_sel_hi:[0,1]
	v_cvt_pk_bf16_f32 v8, v12, v13
	v_cvt_pk_bf16_f32 v9, v14, v15
	v_cvt_pk_bf16_f32 v10, v10, v11
	v_cvt_pk_bf16_f32 v11, v16, v17
	ds_write_b128 v171, v[8:11]
	ds_read_b128 v[8:11], v172
	s_waitcnt lgkmcnt(0)
	global_store_dwordx4 v[20:21], v[8:11], off offset:256 nt
	s_cbranch_vccnz .LBB0_488
	s_andn2_b64 vcc, exec, s[6:7]
	s_cbranch_vccnz .LBB0_487
	s_barrier
	s_branch .LBB0_487
